# baseline (speedup 1.0000x reference)
.Lgu_loop:
	s_waitcnt vmcnt(20)
	v_mov_b32_e32 v8, v10
	v_mov_b32_e32 v9, v11
	ds_bpermute_b32 v192, v4, v8
	ds_bpermute_b32 v193, v4, v8 offset:32
	ds_bpermute_b32 v194, v4, v8 offset:64
	ds_bpermute_b32 v195, v4, v8 offset:96
	ds_bpermute_b32 v196, v4, v8 offset:128
	ds_bpermute_b32 v197, v4, v8 offset:160
	ds_bpermute_b32 v198, v4, v8 offset:192
	ds_bpermute_b32 v199, v4, v8 offset:224
	ds_bpermute_b32 v200, v4, v9
	ds_bpermute_b32 v201, v4, v9 offset:32
	ds_bpermute_b32 v202, v4, v9 offset:64
	ds_bpermute_b32 v203, v4, v9 offset:96
	ds_bpermute_b32 v204, v4, v9 offset:128
	ds_bpermute_b32 v205, v4, v9 offset:160
	ds_bpermute_b32 v206, v4, v9 offset:192
	ds_bpermute_b32 v207, v4, v9 offset:224
	s_mov_b32 s31, s12
	s_add_u32 s26, s22, s31
	s_min_u32 s26, s26, 0x7fff
	s_mov_b32 s42, s26
	s_mul_i32 s31, s12, 2
	s_add_u32 s26, s22, s31
	s_min_u32 s26, s26, 0x7fff
	s_lshl_b32 s30, s26, 9
	s_add_u32 s40, s18, s30
	s_addc_u32 s41, s19, 0
	global_load_dword v10, v1, s[40:41]
	global_load_dword v11, v1, s[40:41] offset:256
	s_waitcnt lgkmcnt(0)
	s_lshl_b32 s30, s42, 12
	s_add_u32 s66, s16, s30
	s_addc_u32 s67, s17, 0
	global_load_dwordx4 v[224:227], v7, s[66:67]
	global_load_dwordx4 v[228:231], v7, s[66:67] offset:16
	global_load_dwordx4 v[232:235], v7, s[66:67] offset:32
	global_load_dwordx4 v[236:239], v7, s[66:67] offset:48
	v_lshl_add_u32 v192, v192, 7, v3
	global_load_dwordx4 v[128:131], v192, s[14:15]
	v_lshl_add_u32 v193, v193, 7, v3
	global_load_dwordx4 v[132:135], v193, s[14:15]
	v_lshl_add_u32 v194, v194, 7, v3
	global_load_dwordx4 v[136:139], v194, s[14:15]
	v_lshl_add_u32 v195, v195, 7, v3
	global_load_dwordx4 v[140:143], v195, s[14:15]
	v_lshl_add_u32 v196, v196, 7, v3
	global_load_dwordx4 v[144:147], v196, s[14:15]
	v_lshl_add_u32 v197, v197, 7, v3
	global_load_dwordx4 v[148:151], v197, s[14:15]
	v_lshl_add_u32 v198, v198, 7, v3
	global_load_dwordx4 v[152:155], v198, s[14:15]
	v_lshl_add_u32 v199, v199, 7, v3
	global_load_dwordx4 v[156:159], v199, s[14:15]
	v_lshl_add_u32 v200, v200, 7, v3
	global_load_dwordx4 v[160:163], v200, s[14:15]
	v_lshl_add_u32 v201, v201, 7, v3
	global_load_dwordx4 v[164:167], v201, s[14:15]
	v_lshl_add_u32 v202, v202, 7, v3
	global_load_dwordx4 v[168:171], v202, s[14:15]
	v_lshl_add_u32 v203, v203, 7, v3
	global_load_dwordx4 v[172:175], v203, s[14:15]
	v_lshl_add_u32 v204, v204, 7, v3
	global_load_dwordx4 v[176:179], v204, s[14:15]
	v_lshl_add_u32 v205, v205, 7, v3
	global_load_dwordx4 v[180:183], v205, s[14:15]
	v_lshl_add_u32 v206, v206, 7, v3
	global_load_dwordx4 v[184:187], v206, s[14:15]
	v_lshl_add_u32 v207, v207, 7, v3
	global_load_dwordx4 v[188:191], v207, s[14:15]
	s_waitcnt vmcnt(37)
	v_cvt_pk_f32_fp8_e32 v[40:41], v64
	v_cvt_pk_f32_fp8_sdwa v[42:43], v64 src0_sel:WORD_1
	v_cvt_pk_f32_fp8_e32 v[44:45], v65
	v_cvt_pk_f32_fp8_sdwa v[46:47], v65 src0_sel:WORD_1
	v_cvt_pk_f32_fp8_e32 v[48:49], v66
	v_cvt_pk_f32_fp8_sdwa v[50:51], v66 src0_sel:WORD_1
	v_cvt_pk_f32_fp8_e32 v[52:53], v67
	v_cvt_pk_f32_fp8_sdwa v[54:55], v67 src0_sel:WORD_1
	v_pk_mul_f32 v[24:25], v[40:41], v[208:209]
	v_pk_fma_f32 v[24:25], v[42:43], v[210:211], v[24:25]
	v_pk_fma_f32 v[24:25], v[44:45], v[212:213], v[24:25]
	v_pk_fma_f32 v[24:25], v[46:47], v[214:215], v[24:25]
	v_pk_fma_f32 v[24:25], v[48:49], v[216:217], v[24:25]
	v_pk_fma_f32 v[24:25], v[50:51], v[218:219], v[24:25]
	v_pk_fma_f32 v[24:25], v[52:53], v[220:221], v[24:25]
	v_pk_fma_f32 v[24:25], v[54:55], v[222:223], v[24:25]
	v_add_f32_e32 v56, v24, v25
	ds_write_b32 v5, v56
	s_waitcnt vmcnt(36)
	v_cvt_pk_f32_fp8_e32 v[40:41], v68
	v_cvt_pk_f32_fp8_sdwa v[42:43], v68 src0_sel:WORD_1
	v_cvt_pk_f32_fp8_e32 v[44:45], v69
	v_cvt_pk_f32_fp8_sdwa v[46:47], v69 src0_sel:WORD_1
	v_cvt_pk_f32_fp8_e32 v[48:49], v70
	v_cvt_pk_f32_fp8_sdwa v[50:51], v70 src0_sel:WORD_1
	v_cvt_pk_f32_fp8_e32 v[52:53], v71
	v_cvt_pk_f32_fp8_sdwa v[54:55], v71 src0_sel:WORD_1
	v_pk_mul_f32 v[24:25], v[40:41], v[208:209]
	v_pk_fma_f32 v[24:25], v[42:43], v[210:211], v[24:25]
	v_pk_fma_f32 v[24:25], v[44:45], v[212:213], v[24:25]
	v_pk_fma_f32 v[24:25], v[46:47], v[214:215], v[24:25]
	v_pk_fma_f32 v[24:25], v[48:49], v[216:217], v[24:25]
	v_pk_fma_f32 v[24:25], v[50:51], v[218:219], v[24:25]
	v_pk_fma_f32 v[24:25], v[52:53], v[220:221], v[24:25]
	v_pk_fma_f32 v[24:25], v[54:55], v[222:223], v[24:25]
	v_add_f32_e32 v56, v24, v25
	ds_write_b32 v5, v56 offset:256
	s_waitcnt vmcnt(35)
	v_cvt_pk_f32_fp8_e32 v[40:41], v72
	v_cvt_pk_f32_fp8_sdwa v[42:43], v72 src0_sel:WORD_1
	v_cvt_pk_f32_fp8_e32 v[44:45], v73
	v_cvt_pk_f32_fp8_sdwa v[46:47], v73 src0_sel:WORD_1
	v_cvt_pk_f32_fp8_e32 v[48:49], v74
	v_cvt_pk_f32_fp8_sdwa v[50:51], v74 src0_sel:WORD_1
	v_cvt_pk_f32_fp8_e32 v[52:53], v75
	v_cvt_pk_f32_fp8_sdwa v[54:55], v75 src0_sel:WORD_1
	v_pk_mul_f32 v[24:25], v[40:41], v[208:209]
	v_pk_fma_f32 v[24:25], v[42:43], v[210:211], v[24:25]
	v_pk_fma_f32 v[24:25], v[44:45], v[212:213], v[24:25]
	v_pk_fma_f32 v[24:25], v[46:47], v[214:215], v[24:25]
	v_pk_fma_f32 v[24:25], v[48:49], v[216:217], v[24:25]
	v_pk_fma_f32 v[24:25], v[50:51], v[218:219], v[24:25]
	v_pk_fma_f32 v[24:25], v[52:53], v[220:221], v[24:25]
	v_pk_fma_f32 v[24:25], v[54:55], v[222:223], v[24:25]
	v_add_f32_e32 v56, v24, v25
	ds_write_b32 v5, v56 offset:512
	s_waitcnt vmcnt(34)
	v_cvt_pk_f32_fp8_e32 v[40:41], v76
	v_cvt_pk_f32_fp8_sdwa v[42:43], v76 src0_sel:WORD_1
	v_cvt_pk_f32_fp8_e32 v[44:45], v77
	v_cvt_pk_f32_fp8_sdwa v[46:47], v77 src0_sel:WORD_1
	v_cvt_pk_f32_fp8_e32 v[48:49], v78
	v_cvt_pk_f32_fp8_sdwa v[50:51], v78 src0_sel:WORD_1
	v_cvt_pk_f32_fp8_e32 v[52:53], v79
	v_cvt_pk_f32_fp8_sdwa v[54:55], v79 src0_sel:WORD_1
	v_pk_mul_f32 v[24:25], v[40:41], v[208:209]
	v_pk_fma_f32 v[24:25], v[42:43], v[210:211], v[24:25]
	v_pk_fma_f32 v[24:25], v[44:45], v[212:213], v[24:25]
	v_pk_fma_f32 v[24:25], v[46:47], v[214:215], v[24:25]
	v_pk_fma_f32 v[24:25], v[48:49], v[216:217], v[24:25]
	v_pk_fma_f32 v[24:25], v[50:51], v[218:219], v[24:25]
	v_pk_fma_f32 v[24:25], v[52:53], v[220:221], v[24:25]
	v_pk_fma_f32 v[24:25], v[54:55], v[222:223], v[24:25]
	v_add_f32_e32 v56, v24, v25
	ds_write_b32 v5, v56 offset:768
	s_waitcnt vmcnt(33)
	v_cvt_pk_f32_fp8_e32 v[40:41], v80
	v_cvt_pk_f32_fp8_sdwa v[42:43], v80 src0_sel:WORD_1
	v_cvt_pk_f32_fp8_e32 v[44:45], v81
	v_cvt_pk_f32_fp8_sdwa v[46:47], v81 src0_sel:WORD_1
	v_cvt_pk_f32_fp8_e32 v[48:49], v82
	v_cvt_pk_f32_fp8_sdwa v[50:51], v82 src0_sel:WORD_1
	v_cvt_pk_f32_fp8_e32 v[52:53], v83
	v_cvt_pk_f32_fp8_sdwa v[54:55], v83 src0_sel:WORD_1
	v_pk_mul_f32 v[24:25], v[40:41], v[208:209]
	v_pk_fma_f32 v[24:25], v[42:43], v[210:211], v[24:25]
	v_pk_fma_f32 v[24:25], v[44:45], v[212:213], v[24:25]
	v_pk_fma_f32 v[24:25], v[46:47], v[214:215], v[24:25]
	v_pk_fma_f32 v[24:25], v[48:49], v[216:217], v[24:25]
	v_pk_fma_f32 v[24:25], v[50:51], v[218:219], v[24:25]
	v_pk_fma_f32 v[24:25], v[52:53], v[220:221], v[24:25]
	v_pk_fma_f32 v[24:25], v[54:55], v[222:223], v[24:25]
	v_add_f32_e32 v56, v24, v25
	ds_write_b32 v5, v56 offset:1024
	s_waitcnt vmcnt(32)
	v_cvt_pk_f32_fp8_e32 v[40:41], v84
	v_cvt_pk_f32_fp8_sdwa v[42:43], v84 src0_sel:WORD_1
	v_cvt_pk_f32_fp8_e32 v[44:45], v85
	v_cvt_pk_f32_fp8_sdwa v[46:47], v85 src0_sel:WORD_1
	v_cvt_pk_f32_fp8_e32 v[48:49], v86
	v_cvt_pk_f32_fp8_sdwa v[50:51], v86 src0_sel:WORD_1
	v_cvt_pk_f32_fp8_e32 v[52:53], v87
	v_cvt_pk_f32_fp8_sdwa v[54:55], v87 src0_sel:WORD_1
	v_pk_mul_f32 v[24:25], v[40:41], v[208:209]
	v_pk_fma_f32 v[24:25], v[42:43], v[210:211], v[24:25]
	v_pk_fma_f32 v[24:25], v[44:45], v[212:213], v[24:25]
	v_pk_fma_f32 v[24:25], v[46:47], v[214:215], v[24:25]
	v_pk_fma_f32 v[24:25], v[48:49], v[216:217], v[24:25]
	v_pk_fma_f32 v[24:25], v[50:51], v[218:219], v[24:25]
	v_pk_fma_f32 v[24:25], v[52:53], v[220:221], v[24:25]
	v_pk_fma_f32 v[24:25], v[54:55], v[222:223], v[24:25]
	v_add_f32_e32 v56, v24, v25
	ds_write_b32 v5, v56 offset:1280
	s_waitcnt vmcnt(31)
	v_cvt_pk_f32_fp8_e32 v[40:41], v88
	v_cvt_pk_f32_fp8_sdwa v[42:43], v88 src0_sel:WORD_1
	v_cvt_pk_f32_fp8_e32 v[44:45], v89
	v_cvt_pk_f32_fp8_sdwa v[46:47], v89 src0_sel:WORD_1
	v_cvt_pk_f32_fp8_e32 v[48:49], v90
	v_cvt_pk_f32_fp8_sdwa v[50:51], v90 src0_sel:WORD_1
	v_cvt_pk_f32_fp8_e32 v[52:53], v91
	v_cvt_pk_f32_fp8_sdwa v[54:55], v91 src0_sel:WORD_1
	v_pk_mul_f32 v[24:25], v[40:41], v[208:209]
	v_pk_fma_f32 v[24:25], v[42:43], v[210:211], v[24:25]
	v_pk_fma_f32 v[24:25], v[44:45], v[212:213], v[24:25]
	v_pk_fma_f32 v[24:25], v[46:47], v[214:215], v[24:25]
	v_pk_fma_f32 v[24:25], v[48:49], v[216:217], v[24:25]
	v_pk_fma_f32 v[24:25], v[50:51], v[218:219], v[24:25]
	v_pk_fma_f32 v[24:25], v[52:53], v[220:221], v[24:25]
	v_pk_fma_f32 v[24:25], v[54:55], v[222:223], v[24:25]
	v_add_f32_e32 v56, v24, v25
	ds_write_b32 v5, v56 offset:1536
	s_waitcnt vmcnt(30)
	v_cvt_pk_f32_fp8_e32 v[40:41], v92
	v_cvt_pk_f32_fp8_sdwa v[42:43], v92 src0_sel:WORD_1
	v_cvt_pk_f32_fp8_e32 v[44:45], v93
	v_cvt_pk_f32_fp8_sdwa v[46:47], v93 src0_sel:WORD_1
	v_cvt_pk_f32_fp8_e32 v[48:49], v94
	v_cvt_pk_f32_fp8_sdwa v[50:51], v94 src0_sel:WORD_1
	v_cvt_pk_f32_fp8_e32 v[52:53], v95
	v_cvt_pk_f32_fp8_sdwa v[54:55], v95 src0_sel:WORD_1
	v_pk_mul_f32 v[24:25], v[40:41], v[208:209]
	v_pk_fma_f32 v[24:25], v[42:43], v[210:211], v[24:25]
	v_pk_fma_f32 v[24:25], v[44:45], v[212:213], v[24:25]
	v_pk_fma_f32 v[24:25], v[46:47], v[214:215], v[24:25]
	v_pk_fma_f32 v[24:25], v[48:49], v[216:217], v[24:25]
	v_pk_fma_f32 v[24:25], v[50:51], v[218:219], v[24:25]
	v_pk_fma_f32 v[24:25], v[52:53], v[220:221], v[24:25]
	v_pk_fma_f32 v[24:25], v[54:55], v[222:223], v[24:25]
	v_add_f32_e32 v56, v24, v25
	ds_write_b32 v5, v56 offset:1792
	s_waitcnt vmcnt(29)
	v_cvt_pk_f32_fp8_e32 v[40:41], v96
	v_cvt_pk_f32_fp8_sdwa v[42:43], v96 src0_sel:WORD_1
	v_cvt_pk_f32_fp8_e32 v[44:45], v97
	v_cvt_pk_f32_fp8_sdwa v[46:47], v97 src0_sel:WORD_1
	v_cvt_pk_f32_fp8_e32 v[48:49], v98
	v_cvt_pk_f32_fp8_sdwa v[50:51], v98 src0_sel:WORD_1
	v_cvt_pk_f32_fp8_e32 v[52:53], v99
	v_cvt_pk_f32_fp8_sdwa v[54:55], v99 src0_sel:WORD_1
	v_pk_mul_f32 v[24:25], v[40:41], v[208:209]
	v_pk_fma_f32 v[24:25], v[42:43], v[210:211], v[24:25]
	v_pk_fma_f32 v[24:25], v[44:45], v[212:213], v[24:25]
	v_pk_fma_f32 v[24:25], v[46:47], v[214:215], v[24:25]
	v_pk_fma_f32 v[24:25], v[48:49], v[216:217], v[24:25]
	v_pk_fma_f32 v[24:25], v[50:51], v[218:219], v[24:25]
	v_pk_fma_f32 v[24:25], v[52:53], v[220:221], v[24:25]
	v_pk_fma_f32 v[24:25], v[54:55], v[222:223], v[24:25]
	v_add_f32_e32 v56, v24, v25
	ds_write_b32 v5, v56 offset:2048
	s_waitcnt vmcnt(28)
	v_cvt_pk_f32_fp8_e32 v[40:41], v100
	v_cvt_pk_f32_fp8_sdwa v[42:43], v100 src0_sel:WORD_1
	v_cvt_pk_f32_fp8_e32 v[44:45], v101
	v_cvt_pk_f32_fp8_sdwa v[46:47], v101 src0_sel:WORD_1
	v_cvt_pk_f32_fp8_e32 v[48:49], v102
	v_cvt_pk_f32_fp8_sdwa v[50:51], v102 src0_sel:WORD_1
	v_cvt_pk_f32_fp8_e32 v[52:53], v103
	v_cvt_pk_f32_fp8_sdwa v[54:55], v103 src0_sel:WORD_1
	v_pk_mul_f32 v[24:25], v[40:41], v[208:209]
	v_pk_fma_f32 v[24:25], v[42:43], v[210:211], v[24:25]
	v_pk_fma_f32 v[24:25], v[44:45], v[212:213], v[24:25]
	v_pk_fma_f32 v[24:25], v[46:47], v[214:215], v[24:25]
	v_pk_fma_f32 v[24:25], v[48:49], v[216:217], v[24:25]
	v_pk_fma_f32 v[24:25], v[50:51], v[218:219], v[24:25]
	v_pk_fma_f32 v[24:25], v[52:53], v[220:221], v[24:25]
	v_pk_fma_f32 v[24:25], v[54:55], v[222:223], v[24:25]
	v_add_f32_e32 v56, v24, v25
	ds_write_b32 v5, v56 offset:2304
	s_waitcnt vmcnt(27)
	v_cvt_pk_f32_fp8_e32 v[40:41], v104
	v_cvt_pk_f32_fp8_sdwa v[42:43], v104 src0_sel:WORD_1
	v_cvt_pk_f32_fp8_e32 v[44:45], v105
	v_cvt_pk_f32_fp8_sdwa v[46:47], v105 src0_sel:WORD_1
	v_cvt_pk_f32_fp8_e32 v[48:49], v106
	v_cvt_pk_f32_fp8_sdwa v[50:51], v106 src0_sel:WORD_1
	v_cvt_pk_f32_fp8_e32 v[52:53], v107
	v_cvt_pk_f32_fp8_sdwa v[54:55], v107 src0_sel:WORD_1
	v_pk_mul_f32 v[24:25], v[40:41], v[208:209]
	v_pk_fma_f32 v[24:25], v[42:43], v[210:211], v[24:25]
	v_pk_fma_f32 v[24:25], v[44:45], v[212:213], v[24:25]
	v_pk_fma_f32 v[24:25], v[46:47], v[214:215], v[24:25]
	v_pk_fma_f32 v[24:25], v[48:49], v[216:217], v[24:25]
	v_pk_fma_f32 v[24:25], v[50:51], v[218:219], v[24:25]
	v_pk_fma_f32 v[24:25], v[52:53], v[220:221], v[24:25]
	v_pk_fma_f32 v[24:25], v[54:55], v[222:223], v[24:25]
	v_add_f32_e32 v56, v24, v25
	ds_write_b32 v5, v56 offset:2560
	s_waitcnt vmcnt(26)
	v_cvt_pk_f32_fp8_e32 v[40:41], v108
	v_cvt_pk_f32_fp8_sdwa v[42:43], v108 src0_sel:WORD_1
	v_cvt_pk_f32_fp8_e32 v[44:45], v109
	v_cvt_pk_f32_fp8_sdwa v[46:47], v109 src0_sel:WORD_1
	v_cvt_pk_f32_fp8_e32 v[48:49], v110
	v_cvt_pk_f32_fp8_sdwa v[50:51], v110 src0_sel:WORD_1
	v_cvt_pk_f32_fp8_e32 v[52:53], v111
	v_cvt_pk_f32_fp8_sdwa v[54:55], v111 src0_sel:WORD_1
	v_pk_mul_f32 v[24:25], v[40:41], v[208:209]
	v_pk_fma_f32 v[24:25], v[42:43], v[210:211], v[24:25]
	v_pk_fma_f32 v[24:25], v[44:45], v[212:213], v[24:25]
	v_pk_fma_f32 v[24:25], v[46:47], v[214:215], v[24:25]
	v_pk_fma_f32 v[24:25], v[48:49], v[216:217], v[24:25]
	v_pk_fma_f32 v[24:25], v[50:51], v[218:219], v[24:25]
	v_pk_fma_f32 v[24:25], v[52:53], v[220:221], v[24:25]
	v_pk_fma_f32 v[24:25], v[54:55], v[222:223], v[24:25]
	v_add_f32_e32 v56, v24, v25
	ds_write_b32 v5, v56 offset:2816
	s_waitcnt vmcnt(25)
	v_cvt_pk_f32_fp8_e32 v[40:41], v112
	v_cvt_pk_f32_fp8_sdwa v[42:43], v112 src0_sel:WORD_1
	v_cvt_pk_f32_fp8_e32 v[44:45], v113
	v_cvt_pk_f32_fp8_sdwa v[46:47], v113 src0_sel:WORD_1
	v_cvt_pk_f32_fp8_e32 v[48:49], v114
	v_cvt_pk_f32_fp8_sdwa v[50:51], v114 src0_sel:WORD_1
	v_cvt_pk_f32_fp8_e32 v[52:53], v115
	v_cvt_pk_f32_fp8_sdwa v[54:55], v115 src0_sel:WORD_1
	v_pk_mul_f32 v[24:25], v[40:41], v[208:209]
	v_pk_fma_f32 v[24:25], v[42:43], v[210:211], v[24:25]
	v_pk_fma_f32 v[24:25], v[44:45], v[212:213], v[24:25]
	v_pk_fma_f32 v[24:25], v[46:47], v[214:215], v[24:25]
	v_pk_fma_f32 v[24:25], v[48:49], v[216:217], v[24:25]
	v_pk_fma_f32 v[24:25], v[50:51], v[218:219], v[24:25]
	v_pk_fma_f32 v[24:25], v[52:53], v[220:221], v[24:25]
	v_pk_fma_f32 v[24:25], v[54:55], v[222:223], v[24:25]
	v_add_f32_e32 v56, v24, v25
	ds_write_b32 v5, v56 offset:3072
	s_waitcnt vmcnt(24)
	v_cvt_pk_f32_fp8_e32 v[40:41], v116
	v_cvt_pk_f32_fp8_sdwa v[42:43], v116 src0_sel:WORD_1
	v_cvt_pk_f32_fp8_e32 v[44:45], v117
	v_cvt_pk_f32_fp8_sdwa v[46:47], v117 src0_sel:WORD_1
	v_cvt_pk_f32_fp8_e32 v[48:49], v118
	v_cvt_pk_f32_fp8_sdwa v[50:51], v118 src0_sel:WORD_1
	v_cvt_pk_f32_fp8_e32 v[52:53], v119
	v_cvt_pk_f32_fp8_sdwa v[54:55], v119 src0_sel:WORD_1
	v_pk_mul_f32 v[24:25], v[40:41], v[208:209]
	v_pk_fma_f32 v[24:25], v[42:43], v[210:211], v[24:25]
	v_pk_fma_f32 v[24:25], v[44:45], v[212:213], v[24:25]
	v_pk_fma_f32 v[24:25], v[46:47], v[214:215], v[24:25]
	v_pk_fma_f32 v[24:25], v[48:49], v[216:217], v[24:25]
	v_pk_fma_f32 v[24:25], v[50:51], v[218:219], v[24:25]
	v_pk_fma_f32 v[24:25], v[52:53], v[220:221], v[24:25]
	v_pk_fma_f32 v[24:25], v[54:55], v[222:223], v[24:25]
	v_add_f32_e32 v56, v24, v25
	ds_write_b32 v5, v56 offset:3328
	s_waitcnt vmcnt(23)
	v_cvt_pk_f32_fp8_e32 v[40:41], v120
	v_cvt_pk_f32_fp8_sdwa v[42:43], v120 src0_sel:WORD_1
	v_cvt_pk_f32_fp8_e32 v[44:45], v121
	v_cvt_pk_f32_fp8_sdwa v[46:47], v121 src0_sel:WORD_1
	v_cvt_pk_f32_fp8_e32 v[48:49], v122
	v_cvt_pk_f32_fp8_sdwa v[50:51], v122 src0_sel:WORD_1
	v_cvt_pk_f32_fp8_e32 v[52:53], v123
	v_cvt_pk_f32_fp8_sdwa v[54:55], v123 src0_sel:WORD_1
	v_pk_mul_f32 v[24:25], v[40:41], v[208:209]
	v_pk_fma_f32 v[24:25], v[42:43], v[210:211], v[24:25]
	v_pk_fma_f32 v[24:25], v[44:45], v[212:213], v[24:25]
	v_pk_fma_f32 v[24:25], v[46:47], v[214:215], v[24:25]
	v_pk_fma_f32 v[24:25], v[48:49], v[216:217], v[24:25]
	v_pk_fma_f32 v[24:25], v[50:51], v[218:219], v[24:25]
	v_pk_fma_f32 v[24:25], v[52:53], v[220:221], v[24:25]
	v_pk_fma_f32 v[24:25], v[54:55], v[222:223], v[24:25]
	v_add_f32_e32 v56, v24, v25
	ds_write_b32 v5, v56 offset:3584
	s_waitcnt vmcnt(22)
	v_cvt_pk_f32_fp8_e32 v[40:41], v124
	v_cvt_pk_f32_fp8_sdwa v[42:43], v124 src0_sel:WORD_1
	v_cvt_pk_f32_fp8_e32 v[44:45], v125
	v_cvt_pk_f32_fp8_sdwa v[46:47], v125 src0_sel:WORD_1
	v_cvt_pk_f32_fp8_e32 v[48:49], v126
	v_cvt_pk_f32_fp8_sdwa v[50:51], v126 src0_sel:WORD_1
	v_cvt_pk_f32_fp8_e32 v[52:53], v127
	v_cvt_pk_f32_fp8_sdwa v[54:55], v127 src0_sel:WORD_1
	v_pk_mul_f32 v[24:25], v[40:41], v[208:209]
	v_pk_fma_f32 v[24:25], v[42:43], v[210:211], v[24:25]
	v_pk_fma_f32 v[24:25], v[44:45], v[212:213], v[24:25]
	v_pk_fma_f32 v[24:25], v[46:47], v[214:215], v[24:25]
	v_pk_fma_f32 v[24:25], v[48:49], v[216:217], v[24:25]
	v_pk_fma_f32 v[24:25], v[50:51], v[218:219], v[24:25]
	v_pk_fma_f32 v[24:25], v[52:53], v[220:221], v[24:25]
	v_pk_fma_f32 v[24:25], v[54:55], v[222:223], v[24:25]
	v_add_f32_e32 v56, v24, v25
	ds_write_b32 v5, v56 offset:3840
	ds_read_b128 v[40:43], v6
	ds_read_b128 v[44:47], v6 offset:16
	ds_read_b128 v[48:51], v6 offset:2048
	ds_read_b128 v[52:55], v6 offset:2064
	s_waitcnt lgkmcnt(2)
	v_add_f32_e32 v40, v40, v41
	v_add_f32_e32 v40, v40, v42
	v_add_f32_e32 v40, v40, v43
	v_add_f32_e32 v40, v40, v44
	v_add_f32_e32 v40, v40, v45
	v_add_f32_e32 v40, v40, v46
	v_add_f32_e32 v40, v40, v47
	s_waitcnt lgkmcnt(0)
	v_add_f32_e32 v48, v48, v49
	v_add_f32_e32 v48, v48, v50
	v_add_f32_e32 v48, v48, v51
	v_add_f32_e32 v48, v48, v52
	v_add_f32_e32 v48, v48, v53
	v_add_f32_e32 v48, v48, v54
	v_add_f32_e32 v48, v48, v55
	s_lshl_b32 s30, s22, 12
	s_add_u32 s66, s20, s30
	s_addc_u32 s67, s21, 0
	global_store_dword v1, v40, s[66:67]
	global_store_dword v1, v48, s[66:67] offset:256
	s_add_u32 s22, s22, s12
	s_cmp_ge_u32 s22, 0x8000
	s_cbranch_scc1 .Lgu_done
	s_waitcnt vmcnt(20)
	v_mov_b32_e32 v8, v10
	v_mov_b32_e32 v9, v11
	ds_bpermute_b32 v192, v4, v8
	ds_bpermute_b32 v193, v4, v8 offset:32
	ds_bpermute_b32 v194, v4, v8 offset:64
	ds_bpermute_b32 v195, v4, v8 offset:96
	ds_bpermute_b32 v196, v4, v8 offset:128
	ds_bpermute_b32 v197, v4, v8 offset:160
	ds_bpermute_b32 v198, v4, v8 offset:192
	ds_bpermute_b32 v199, v4, v8 offset:224
	ds_bpermute_b32 v200, v4, v9
	ds_bpermute_b32 v201, v4, v9 offset:32
	ds_bpermute_b32 v202, v4, v9 offset:64
	ds_bpermute_b32 v203, v4, v9 offset:96
	ds_bpermute_b32 v204, v4, v9 offset:128
	ds_bpermute_b32 v205, v4, v9 offset:160
	ds_bpermute_b32 v206, v4, v9 offset:192
	ds_bpermute_b32 v207, v4, v9 offset:224
	s_mov_b32 s31, s12
	s_add_u32 s26, s22, s31
	s_min_u32 s26, s26, 0x7fff
	s_mov_b32 s42, s26
	s_mul_i32 s31, s12, 2
	s_add_u32 s26, s22, s31
	s_min_u32 s26, s26, 0x7fff
	s_lshl_b32 s30, s26, 9
	s_add_u32 s40, s18, s30
	s_addc_u32 s41, s19, 0
	global_load_dword v10, v1, s[40:41]
	global_load_dword v11, v1, s[40:41] offset:256
	s_waitcnt lgkmcnt(0)
	s_lshl_b32 s30, s42, 12
	s_add_u32 s66, s16, s30
	s_addc_u32 s67, s17, 0
	global_load_dwordx4 v[208:211], v7, s[66:67]
	global_load_dwordx4 v[212:215], v7, s[66:67] offset:16
	global_load_dwordx4 v[216:219], v7, s[66:67] offset:32
	global_load_dwordx4 v[220:223], v7, s[66:67] offset:48
	v_lshl_add_u32 v192, v192, 7, v3
	global_load_dwordx4 v[64:67], v192, s[14:15]
	v_lshl_add_u32 v193, v193, 7, v3
	global_load_dwordx4 v[68:71], v193, s[14:15]
	v_lshl_add_u32 v194, v194, 7, v3
	global_load_dwordx4 v[72:75], v194, s[14:15]
	v_lshl_add_u32 v195, v195, 7, v3
	global_load_dwordx4 v[76:79], v195, s[14:15]
	v_lshl_add_u32 v196, v196, 7, v3
	global_load_dwordx4 v[80:83], v196, s[14:15]
	v_lshl_add_u32 v197, v197, 7, v3
	global_load_dwordx4 v[84:87], v197, s[14:15]
	v_lshl_add_u32 v198, v198, 7, v3
	global_load_dwordx4 v[88:91], v198, s[14:15]
	v_lshl_add_u32 v199, v199, 7, v3
	global_load_dwordx4 v[92:95], v199, s[14:15]
	v_lshl_add_u32 v200, v200, 7, v3
	global_load_dwordx4 v[96:99], v200, s[14:15]
	v_lshl_add_u32 v201, v201, 7, v3
	global_load_dwordx4 v[100:103], v201, s[14:15]
	v_lshl_add_u32 v202, v202, 7, v3
	global_load_dwordx4 v[104:107], v202, s[14:15]
	v_lshl_add_u32 v203, v203, 7, v3
	global_load_dwordx4 v[108:111], v203, s[14:15]
	v_lshl_add_u32 v204, v204, 7, v3
	global_load_dwordx4 v[112:115], v204, s[14:15]
	v_lshl_add_u32 v205, v205, 7, v3
	global_load_dwordx4 v[116:119], v205, s[14:15]
	v_lshl_add_u32 v206, v206, 7, v3
	global_load_dwordx4 v[120:123], v206, s[14:15]
	v_lshl_add_u32 v207, v207, 7, v3
	global_load_dwordx4 v[124:127], v207, s[14:15]
	s_waitcnt vmcnt(37)
	v_cvt_pk_f32_fp8_e32 v[40:41], v128
	v_cvt_pk_f32_fp8_sdwa v[42:43], v128 src0_sel:WORD_1
	v_cvt_pk_f32_fp8_e32 v[44:45], v129
	v_cvt_pk_f32_fp8_sdwa v[46:47], v129 src0_sel:WORD_1
	v_cvt_pk_f32_fp8_e32 v[48:49], v130
	v_cvt_pk_f32_fp8_sdwa v[50:51], v130 src0_sel:WORD_1
	v_cvt_pk_f32_fp8_e32 v[52:53], v131
	v_cvt_pk_f32_fp8_sdwa v[54:55], v131 src0_sel:WORD_1
	v_pk_mul_f32 v[24:25], v[40:41], v[224:225]
	v_pk_fma_f32 v[24:25], v[42:43], v[226:227], v[24:25]
	v_pk_fma_f32 v[24:25], v[44:45], v[228:229], v[24:25]
	v_pk_fma_f32 v[24:25], v[46:47], v[230:231], v[24:25]
	v_pk_fma_f32 v[24:25], v[48:49], v[232:233], v[24:25]
	v_pk_fma_f32 v[24:25], v[50:51], v[234:235], v[24:25]
	v_pk_fma_f32 v[24:25], v[52:53], v[236:237], v[24:25]
	v_pk_fma_f32 v[24:25], v[54:55], v[238:239], v[24:25]
	v_add_f32_e32 v56, v24, v25
	ds_write_b32 v5, v56
	s_waitcnt vmcnt(36)
	v_cvt_pk_f32_fp8_e32 v[40:41], v132
	v_cvt_pk_f32_fp8_sdwa v[42:43], v132 src0_sel:WORD_1
	v_cvt_pk_f32_fp8_e32 v[44:45], v133
	v_cvt_pk_f32_fp8_sdwa v[46:47], v133 src0_sel:WORD_1
	v_cvt_pk_f32_fp8_e32 v[48:49], v134
	v_cvt_pk_f32_fp8_sdwa v[50:51], v134 src0_sel:WORD_1
	v_cvt_pk_f32_fp8_e32 v[52:53], v135
	v_cvt_pk_f32_fp8_sdwa v[54:55], v135 src0_sel:WORD_1
	v_pk_mul_f32 v[24:25], v[40:41], v[224:225]
	v_pk_fma_f32 v[24:25], v[42:43], v[226:227], v[24:25]
	v_pk_fma_f32 v[24:25], v[44:45], v[228:229], v[24:25]
	v_pk_fma_f32 v[24:25], v[46:47], v[230:231], v[24:25]
	v_pk_fma_f32 v[24:25], v[48:49], v[232:233], v[24:25]
	v_pk_fma_f32 v[24:25], v[50:51], v[234:235], v[24:25]
	v_pk_fma_f32 v[24:25], v[52:53], v[236:237], v[24:25]
	v_pk_fma_f32 v[24:25], v[54:55], v[238:239], v[24:25]
	v_add_f32_e32 v56, v24, v25
	ds_write_b32 v5, v56 offset:256
	s_waitcnt vmcnt(35)
	v_cvt_pk_f32_fp8_e32 v[40:41], v136
	v_cvt_pk_f32_fp8_sdwa v[42:43], v136 src0_sel:WORD_1
	v_cvt_pk_f32_fp8_e32 v[44:45], v137
	v_cvt_pk_f32_fp8_sdwa v[46:47], v137 src0_sel:WORD_1
	v_cvt_pk_f32_fp8_e32 v[48:49], v138
	v_cvt_pk_f32_fp8_sdwa v[50:51], v138 src0_sel:WORD_1
	v_cvt_pk_f32_fp8_e32 v[52:53], v139
	v_cvt_pk_f32_fp8_sdwa v[54:55], v139 src0_sel:WORD_1
	v_pk_mul_f32 v[24:25], v[40:41], v[224:225]
	v_pk_fma_f32 v[24:25], v[42:43], v[226:227], v[24:25]
	v_pk_fma_f32 v[24:25], v[44:45], v[228:229], v[24:25]
	v_pk_fma_f32 v[24:25], v[46:47], v[230:231], v[24:25]
	v_pk_fma_f32 v[24:25], v[48:49], v[232:233], v[24:25]
	v_pk_fma_f32 v[24:25], v[50:51], v[234:235], v[24:25]
	v_pk_fma_f32 v[24:25], v[52:53], v[236:237], v[24:25]
	v_pk_fma_f32 v[24:25], v[54:55], v[238:239], v[24:25]
	v_add_f32_e32 v56, v24, v25
	ds_write_b32 v5, v56 offset:512
	s_waitcnt vmcnt(34)
	v_cvt_pk_f32_fp8_e32 v[40:41], v140
	v_cvt_pk_f32_fp8_sdwa v[42:43], v140 src0_sel:WORD_1
	v_cvt_pk_f32_fp8_e32 v[44:45], v141
	v_cvt_pk_f32_fp8_sdwa v[46:47], v141 src0_sel:WORD_1
	v_cvt_pk_f32_fp8_e32 v[48:49], v142
	v_cvt_pk_f32_fp8_sdwa v[50:51], v142 src0_sel:WORD_1
	v_cvt_pk_f32_fp8_e32 v[52:53], v143
	v_cvt_pk_f32_fp8_sdwa v[54:55], v143 src0_sel:WORD_1
	v_pk_mul_f32 v[24:25], v[40:41], v[224:225]
	v_pk_fma_f32 v[24:25], v[42:43], v[226:227], v[24:25]
	v_pk_fma_f32 v[24:25], v[44:45], v[228:229], v[24:25]
	v_pk_fma_f32 v[24:25], v[46:47], v[230:231], v[24:25]
	v_pk_fma_f32 v[24:25], v[48:49], v[232:233], v[24:25]
	v_pk_fma_f32 v[24:25], v[50:51], v[234:235], v[24:25]
	v_pk_fma_f32 v[24:25], v[52:53], v[236:237], v[24:25]
	v_pk_fma_f32 v[24:25], v[54:55], v[238:239], v[24:25]
	v_add_f32_e32 v56, v24, v25
	ds_write_b32 v5, v56 offset:768
	s_waitcnt vmcnt(33)
	v_cvt_pk_f32_fp8_e32 v[40:41], v144
	v_cvt_pk_f32_fp8_sdwa v[42:43], v144 src0_sel:WORD_1
	v_cvt_pk_f32_fp8_e32 v[44:45], v145
	v_cvt_pk_f32_fp8_sdwa v[46:47], v145 src0_sel:WORD_1
	v_cvt_pk_f32_fp8_e32 v[48:49], v146
	v_cvt_pk_f32_fp8_sdwa v[50:51], v146 src0_sel:WORD_1
	v_cvt_pk_f32_fp8_e32 v[52:53], v147
	v_cvt_pk_f32_fp8_sdwa v[54:55], v147 src0_sel:WORD_1
	v_pk_mul_f32 v[24:25], v[40:41], v[224:225]
	v_pk_fma_f32 v[24:25], v[42:43], v[226:227], v[24:25]
	v_pk_fma_f32 v[24:25], v[44:45], v[228:229], v[24:25]
	v_pk_fma_f32 v[24:25], v[46:47], v[230:231], v[24:25]
	v_pk_fma_f32 v[24:25], v[48:49], v[232:233], v[24:25]
	v_pk_fma_f32 v[24:25], v[50:51], v[234:235], v[24:25]
	v_pk_fma_f32 v[24:25], v[52:53], v[236:237], v[24:25]
	v_pk_fma_f32 v[24:25], v[54:55], v[238:239], v[24:25]
	v_add_f32_e32 v56, v24, v25
	ds_write_b32 v5, v56 offset:1024
	s_waitcnt vmcnt(32)
	v_cvt_pk_f32_fp8_e32 v[40:41], v148
	v_cvt_pk_f32_fp8_sdwa v[42:43], v148 src0_sel:WORD_1
	v_cvt_pk_f32_fp8_e32 v[44:45], v149
	v_cvt_pk_f32_fp8_sdwa v[46:47], v149 src0_sel:WORD_1
	v_cvt_pk_f32_fp8_e32 v[48:49], v150
	v_cvt_pk_f32_fp8_sdwa v[50:51], v150 src0_sel:WORD_1
	v_cvt_pk_f32_fp8_e32 v[52:53], v151
	v_cvt_pk_f32_fp8_sdwa v[54:55], v151 src0_sel:WORD_1
	v_pk_mul_f32 v[24:25], v[40:41], v[224:225]
	v_pk_fma_f32 v[24:25], v[42:43], v[226:227], v[24:25]
	v_pk_fma_f32 v[24:25], v[44:45], v[228:229], v[24:25]
	v_pk_fma_f32 v[24:25], v[46:47], v[230:231], v[24:25]
	v_pk_fma_f32 v[24:25], v[48:49], v[232:233], v[24:25]
	v_pk_fma_f32 v[24:25], v[50:51], v[234:235], v[24:25]
	v_pk_fma_f32 v[24:25], v[52:53], v[236:237], v[24:25]
	v_pk_fma_f32 v[24:25], v[54:55], v[238:239], v[24:25]
	v_add_f32_e32 v56, v24, v25
	ds_write_b32 v5, v56 offset:1280
	s_waitcnt vmcnt(31)
	v_cvt_pk_f32_fp8_e32 v[40:41], v152
	v_cvt_pk_f32_fp8_sdwa v[42:43], v152 src0_sel:WORD_1
	v_cvt_pk_f32_fp8_e32 v[44:45], v153
	v_cvt_pk_f32_fp8_sdwa v[46:47], v153 src0_sel:WORD_1
	v_cvt_pk_f32_fp8_e32 v[48:49], v154
	v_cvt_pk_f32_fp8_sdwa v[50:51], v154 src0_sel:WORD_1
	v_cvt_pk_f32_fp8_e32 v[52:53], v155
	v_cvt_pk_f32_fp8_sdwa v[54:55], v155 src0_sel:WORD_1
	v_pk_mul_f32 v[24:25], v[40:41], v[224:225]
	v_pk_fma_f32 v[24:25], v[42:43], v[226:227], v[24:25]
	v_pk_fma_f32 v[24:25], v[44:45], v[228:229], v[24:25]
	v_pk_fma_f32 v[24:25], v[46:47], v[230:231], v[24:25]
	v_pk_fma_f32 v[24:25], v[48:49], v[232:233], v[24:25]
	v_pk_fma_f32 v[24:25], v[50:51], v[234:235], v[24:25]
	v_pk_fma_f32 v[24:25], v[52:53], v[236:237], v[24:25]
	v_pk_fma_f32 v[24:25], v[54:55], v[238:239], v[24:25]
	v_add_f32_e32 v56, v24, v25
	ds_write_b32 v5, v56 offset:1536
	s_waitcnt vmcnt(30)
	v_cvt_pk_f32_fp8_e32 v[40:41], v156
	v_cvt_pk_f32_fp8_sdwa v[42:43], v156 src0_sel:WORD_1
	v_cvt_pk_f32_fp8_e32 v[44:45], v157
	v_cvt_pk_f32_fp8_sdwa v[46:47], v157 src0_sel:WORD_1
	v_cvt_pk_f32_fp8_e32 v[48:49], v158
	v_cvt_pk_f32_fp8_sdwa v[50:51], v158 src0_sel:WORD_1
	v_cvt_pk_f32_fp8_e32 v[52:53], v159
	v_cvt_pk_f32_fp8_sdwa v[54:55], v159 src0_sel:WORD_1
	v_pk_mul_f32 v[24:25], v[40:41], v[224:225]
	v_pk_fma_f32 v[24:25], v[42:43], v[226:227], v[24:25]
	v_pk_fma_f32 v[24:25], v[44:45], v[228:229], v[24:25]
	v_pk_fma_f32 v[24:25], v[46:47], v[230:231], v[24:25]
	v_pk_fma_f32 v[24:25], v[48:49], v[232:233], v[24:25]
	v_pk_fma_f32 v[24:25], v[50:51], v[234:235], v[24:25]
	v_pk_fma_f32 v[24:25], v[52:53], v[236:237], v[24:25]
	v_pk_fma_f32 v[24:25], v[54:55], v[238:239], v[24:25]
	v_add_f32_e32 v56, v24, v25
	ds_write_b32 v5, v56 offset:1792
	s_waitcnt vmcnt(29)
	v_cvt_pk_f32_fp8_e32 v[40:41], v160
	v_cvt_pk_f32_fp8_sdwa v[42:43], v160 src0_sel:WORD_1
	v_cvt_pk_f32_fp8_e32 v[44:45], v161
	v_cvt_pk_f32_fp8_sdwa v[46:47], v161 src0_sel:WORD_1
	v_cvt_pk_f32_fp8_e32 v[48:49], v162
	v_cvt_pk_f32_fp8_sdwa v[50:51], v162 src0_sel:WORD_1
	v_cvt_pk_f32_fp8_e32 v[52:53], v163
	v_cvt_pk_f32_fp8_sdwa v[54:55], v163 src0_sel:WORD_1
	v_pk_mul_f32 v[24:25], v[40:41], v[224:225]
	v_pk_fma_f32 v[24:25], v[42:43], v[226:227], v[24:25]
	v_pk_fma_f32 v[24:25], v[44:45], v[228:229], v[24:25]
	v_pk_fma_f32 v[24:25], v[46:47], v[230:231], v[24:25]
	v_pk_fma_f32 v[24:25], v[48:49], v[232:233], v[24:25]
	v_pk_fma_f32 v[24:25], v[50:51], v[234:235], v[24:25]
	v_pk_fma_f32 v[24:25], v[52:53], v[236:237], v[24:25]
	v_pk_fma_f32 v[24:25], v[54:55], v[238:239], v[24:25]
	v_add_f32_e32 v56, v24, v25
	ds_write_b32 v5, v56 offset:2048
	s_waitcnt vmcnt(28)
	v_cvt_pk_f32_fp8_e32 v[40:41], v164
	v_cvt_pk_f32_fp8_sdwa v[42:43], v164 src0_sel:WORD_1
	v_cvt_pk_f32_fp8_e32 v[44:45], v165
	v_cvt_pk_f32_fp8_sdwa v[46:47], v165 src0_sel:WORD_1
	v_cvt_pk_f32_fp8_e32 v[48:49], v166
	v_cvt_pk_f32_fp8_sdwa v[50:51], v166 src0_sel:WORD_1
	v_cvt_pk_f32_fp8_e32 v[52:53], v167
	v_cvt_pk_f32_fp8_sdwa v[54:55], v167 src0_sel:WORD_1
	v_pk_mul_f32 v[24:25], v[40:41], v[224:225]
	v_pk_fma_f32 v[24:25], v[42:43], v[226:227], v[24:25]
	v_pk_fma_f32 v[24:25], v[44:45], v[228:229], v[24:25]
	v_pk_fma_f32 v[24:25], v[46:47], v[230:231], v[24:25]
	v_pk_fma_f32 v[24:25], v[48:49], v[232:233], v[24:25]
	v_pk_fma_f32 v[24:25], v[50:51], v[234:235], v[24:25]
	v_pk_fma_f32 v[24:25], v[52:53], v[236:237], v[24:25]
	v_pk_fma_f32 v[24:25], v[54:55], v[238:239], v[24:25]
	v_add_f32_e32 v56, v24, v25
	ds_write_b32 v5, v56 offset:2304
	s_waitcnt vmcnt(27)
	v_cvt_pk_f32_fp8_e32 v[40:41], v168
	v_cvt_pk_f32_fp8_sdwa v[42:43], v168 src0_sel:WORD_1
	v_cvt_pk_f32_fp8_e32 v[44:45], v169
	v_cvt_pk_f32_fp8_sdwa v[46:47], v169 src0_sel:WORD_1
	v_cvt_pk_f32_fp8_e32 v[48:49], v170
	v_cvt_pk_f32_fp8_sdwa v[50:51], v170 src0_sel:WORD_1
	v_cvt_pk_f32_fp8_e32 v[52:53], v171
	v_cvt_pk_f32_fp8_sdwa v[54:55], v171 src0_sel:WORD_1
	v_pk_mul_f32 v[24:25], v[40:41], v[224:225]
	v_pk_fma_f32 v[24:25], v[42:43], v[226:227], v[24:25]
	v_pk_fma_f32 v[24:25], v[44:45], v[228:229], v[24:25]
	v_pk_fma_f32 v[24:25], v[46:47], v[230:231], v[24:25]
	v_pk_fma_f32 v[24:25], v[48:49], v[232:233], v[24:25]
	v_pk_fma_f32 v[24:25], v[50:51], v[234:235], v[24:25]
	v_pk_fma_f32 v[24:25], v[52:53], v[236:237], v[24:25]
	v_pk_fma_f32 v[24:25], v[54:55], v[238:239], v[24:25]
	v_add_f32_e32 v56, v24, v25
	ds_write_b32 v5, v56 offset:2560
	s_waitcnt vmcnt(26)
	v_cvt_pk_f32_fp8_e32 v[40:41], v172
	v_cvt_pk_f32_fp8_sdwa v[42:43], v172 src0_sel:WORD_1
	v_cvt_pk_f32_fp8_e32 v[44:45], v173
	v_cvt_pk_f32_fp8_sdwa v[46:47], v173 src0_sel:WORD_1
	v_cvt_pk_f32_fp8_e32 v[48:49], v174
	v_cvt_pk_f32_fp8_sdwa v[50:51], v174 src0_sel:WORD_1
	v_cvt_pk_f32_fp8_e32 v[52:53], v175
	v_cvt_pk_f32_fp8_sdwa v[54:55], v175 src0_sel:WORD_1
	v_pk_mul_f32 v[24:25], v[40:41], v[224:225]
	v_pk_fma_f32 v[24:25], v[42:43], v[226:227], v[24:25]
	v_pk_fma_f32 v[24:25], v[44:45], v[228:229], v[24:25]
	v_pk_fma_f32 v[24:25], v[46:47], v[230:231], v[24:25]
	v_pk_fma_f32 v[24:25], v[48:49], v[232:233], v[24:25]
	v_pk_fma_f32 v[24:25], v[50:51], v[234:235], v[24:25]
	v_pk_fma_f32 v[24:25], v[52:53], v[236:237], v[24:25]
	v_pk_fma_f32 v[24:25], v[54:55], v[238:239], v[24:25]
	v_add_f32_e32 v56, v24, v25
	ds_write_b32 v5, v56 offset:2816
	s_waitcnt vmcnt(25)
	v_cvt_pk_f32_fp8_e32 v[40:41], v176
	v_cvt_pk_f32_fp8_sdwa v[42:43], v176 src0_sel:WORD_1
	v_cvt_pk_f32_fp8_e32 v[44:45], v177
	v_cvt_pk_f32_fp8_sdwa v[46:47], v177 src0_sel:WORD_1
	v_cvt_pk_f32_fp8_e32 v[48:49], v178
	v_cvt_pk_f32_fp8_sdwa v[50:51], v178 src0_sel:WORD_1
	v_cvt_pk_f32_fp8_e32 v[52:53], v179
	v_cvt_pk_f32_fp8_sdwa v[54:55], v179 src0_sel:WORD_1
	v_pk_mul_f32 v[24:25], v[40:41], v[224:225]
	v_pk_fma_f32 v[24:25], v[42:43], v[226:227], v[24:25]
	v_pk_fma_f32 v[24:25], v[44:45], v[228:229], v[24:25]
	v_pk_fma_f32 v[24:25], v[46:47], v[230:231], v[24:25]
	v_pk_fma_f32 v[24:25], v[48:49], v[232:233], v[24:25]
	v_pk_fma_f32 v[24:25], v[50:51], v[234:235], v[24:25]
	v_pk_fma_f32 v[24:25], v[52:53], v[236:237], v[24:25]
	v_pk_fma_f32 v[24:25], v[54:55], v[238:239], v[24:25]
	v_add_f32_e32 v56, v24, v25
	ds_write_b32 v5, v56 offset:3072
	s_waitcnt vmcnt(24)
	v_cvt_pk_f32_fp8_e32 v[40:41], v180
	v_cvt_pk_f32_fp8_sdwa v[42:43], v180 src0_sel:WORD_1
	v_cvt_pk_f32_fp8_e32 v[44:45], v181
	v_cvt_pk_f32_fp8_sdwa v[46:47], v181 src0_sel:WORD_1
	v_cvt_pk_f32_fp8_e32 v[48:49], v182
	v_cvt_pk_f32_fp8_sdwa v[50:51], v182 src0_sel:WORD_1
	v_cvt_pk_f32_fp8_e32 v[52:53], v183
	v_cvt_pk_f32_fp8_sdwa v[54:55], v183 src0_sel:WORD_1
	v_pk_mul_f32 v[24:25], v[40:41], v[224:225]
	v_pk_fma_f32 v[24:25], v[42:43], v[226:227], v[24:25]
	v_pk_fma_f32 v[24:25], v[44:45], v[228:229], v[24:25]
	v_pk_fma_f32 v[24:25], v[46:47], v[230:231], v[24:25]
	v_pk_fma_f32 v[24:25], v[48:49], v[232:233], v[24:25]
	v_pk_fma_f32 v[24:25], v[50:51], v[234:235], v[24:25]
	v_pk_fma_f32 v[24:25], v[52:53], v[236:237], v[24:25]
	v_pk_fma_f32 v[24:25], v[54:55], v[238:239], v[24:25]
	v_add_f32_e32 v56, v24, v25
	ds_write_b32 v5, v56 offset:3328
	s_waitcnt vmcnt(23)
	v_cvt_pk_f32_fp8_e32 v[40:41], v184
	v_cvt_pk_f32_fp8_sdwa v[42:43], v184 src0_sel:WORD_1
	v_cvt_pk_f32_fp8_e32 v[44:45], v185
	v_cvt_pk_f32_fp8_sdwa v[46:47], v185 src0_sel:WORD_1
	v_cvt_pk_f32_fp8_e32 v[48:49], v186
	v_cvt_pk_f32_fp8_sdwa v[50:51], v186 src0_sel:WORD_1
	v_cvt_pk_f32_fp8_e32 v[52:53], v187
	v_cvt_pk_f32_fp8_sdwa v[54:55], v187 src0_sel:WORD_1
	v_pk_mul_f32 v[24:25], v[40:41], v[224:225]
	v_pk_fma_f32 v[24:25], v[42:43], v[226:227], v[24:25]
	v_pk_fma_f32 v[24:25], v[44:45], v[228:229], v[24:25]
	v_pk_fma_f32 v[24:25], v[46:47], v[230:231], v[24:25]
	v_pk_fma_f32 v[24:25], v[48:49], v[232:233], v[24:25]
	v_pk_fma_f32 v[24:25], v[50:51], v[234:235], v[24:25]
	v_pk_fma_f32 v[24:25], v[52:53], v[236:237], v[24:25]
	v_pk_fma_f32 v[24:25], v[54:55], v[238:239], v[24:25]
	v_add_f32_e32 v56, v24, v25
	ds_write_b32 v5, v56 offset:3584
	s_waitcnt vmcnt(22)
	v_cvt_pk_f32_fp8_e32 v[40:41], v188
	v_cvt_pk_f32_fp8_sdwa v[42:43], v188 src0_sel:WORD_1
	v_cvt_pk_f32_fp8_e32 v[44:45], v189
	v_cvt_pk_f32_fp8_sdwa v[46:47], v189 src0_sel:WORD_1
	v_cvt_pk_f32_fp8_e32 v[48:49], v190
	v_cvt_pk_f32_fp8_sdwa v[50:51], v190 src0_sel:WORD_1
	v_cvt_pk_f32_fp8_e32 v[52:53], v191
	v_cvt_pk_f32_fp8_sdwa v[54:55], v191 src0_sel:WORD_1
	v_pk_mul_f32 v[24:25], v[40:41], v[224:225]
	v_pk_fma_f32 v[24:25], v[42:43], v[226:227], v[24:25]
	v_pk_fma_f32 v[24:25], v[44:45], v[228:229], v[24:25]
	v_pk_fma_f32 v[24:25], v[46:47], v[230:231], v[24:25]
	v_pk_fma_f32 v[24:25], v[48:49], v[232:233], v[24:25]
	v_pk_fma_f32 v[24:25], v[50:51], v[234:235], v[24:25]
	v_pk_fma_f32 v[24:25], v[52:53], v[236:237], v[24:25]
	v_pk_fma_f32 v[24:25], v[54:55], v[238:239], v[24:25]
	v_add_f32_e32 v56, v24, v25
	ds_write_b32 v5, v56 offset:3840
	ds_read_b128 v[40:43], v6
	ds_read_b128 v[44:47], v6 offset:16
	ds_read_b128 v[48:51], v6 offset:2048
	ds_read_b128 v[52:55], v6 offset:2064
	s_waitcnt lgkmcnt(2)
	v_add_f32_e32 v40, v40, v41
	v_add_f32_e32 v40, v40, v42
	v_add_f32_e32 v40, v40, v43
	v_add_f32_e32 v40, v40, v44
	v_add_f32_e32 v40, v40, v45
	v_add_f32_e32 v40, v40, v46
	v_add_f32_e32 v40, v40, v47
	s_waitcnt lgkmcnt(0)
	v_add_f32_e32 v48, v48, v49
	v_add_f32_e32 v48, v48, v50
	v_add_f32_e32 v48, v48, v51
	v_add_f32_e32 v48, v48, v52
	v_add_f32_e32 v48, v48, v53
	v_add_f32_e32 v48, v48, v54
	v_add_f32_e32 v48, v48, v55
	s_lshl_b32 s30, s22, 12
	s_add_u32 s66, s20, s30
	s_addc_u32 s67, s21, 0
	global_store_dword v1, v40, s[66:67]
	global_store_dword v1, v48, s[66:67] offset:256
	s_add_u32 s22, s22, s12
	s_cmp_ge_u32 s22, 0x8000
	s_cbranch_scc0 .Lgu_loop
